# m27 + every CU (followers and non-last XCD leaders) leaves the grid barrier when the TOP arrival counter reaches its target (no TOPGEN release hop)
# speedup vs baseline: 1.0017x; 1.0017x over previous
; __device__ __forceinline__ unsigned xb_ld(unsigned* p)              { return __hip_atomic_load(p, __ATOMIC_RELAXED, __HIP_MEMORY_SCOPE_AGENT); }
; #define XB_SPIN(cond, bar) do { unsigned _sp = 0; while (cond) { __builtin_amdgcn_s_sleep(1); \
;     if ((++_sp & 255u) == 0u) { if (xb_ld(&(bar)[XB_TMO])) break; if (_sp > XB_SPIN_CAP) { atomicAdd(&(bar)[XB_TMO], 1u); break; } } } } while (0)
; __device__ __forceinline__ void xcd_barrier(const XcdBarrier& b) {
;     ...
;             XB_SPIN(xb_ld(&bar[XB_XGEN(b.x)]) == gen, bar);
.LBB11_395:
	s_or_b64 exec, exec, s[6:7]
	v_cvt_f32_u32_e32 v6, v4
	s_waitcnt vmcnt(0)
	v_readfirstlane_b32 s1, v5
	v_sub_u32_e32 v5, 0, v4
	v_rcp_iflag_f32_e32 v6, v6
	v_add_u32_e32 v7, s1, v1
	v_mul_f32_e32 v6, 0x4f7ffffe, v6
	v_cvt_u32_f32_e32 v6, v6
	v_mul_lo_u32 v1, v5, v6
	v_mul_hi_u32 v1, v6, v1
	v_add_u32_e32 v1, v6, v1
	v_mul_hi_u32 v1, v7, v1
	v_mul_lo_u32 v5, v1, v4
	v_sub_u32_e32 v5, v7, v5
	v_add_u32_e32 v6, 1, v1
	v_cmp_ge_u32_e32 vcc, v5, v4
	s_nop 1
	v_cndmask_b32_e32 v1, v1, v6, vcc
	v_sub_u32_e32 v6, v5, v4
	v_cndmask_b32_e32 v5, v5, v6, vcc
	v_add_u32_e32 v6, 1, v1
	v_cmp_ge_u32_e32 vcc, v5, v4
	v_add_u32_e32 v5, 1, v7
	s_nop 0
	v_cndmask_b32_e32 v1, v1, v6, vcc
	v_mul_lo_u32 v6, v4, v1
	v_add_u32_e32 v4, v6, v4
	v_cmp_ne_u32_e32 vcc, v5, v4
	s_and_saveexec_b64 s[6:7], vcc
	s_xor_b64 s[6:7], exec, s[6:7]
	s_cbranch_execz .LBB11_409
	v_readlane_b32 s101, v255, 13
	v_readlane_b32 s8, v255, 14
	s_nop 3
	s_cmp_eq_u32 s100, 1
	s_cselect_b32 s101, s8, s101
	s_cselect_b32 s8, 1, 3
	s_add_i32 s101, s101, 1
	s_lshl_b32 s101, s101, s8
	v_mov_b32_e32 v1, s101
	v_readlane_b32 s8, v250, 49
	v_readlane_b32 s9, v250, 50
	s_waitcnt lgkmcnt(0)
	s_nop 3
	buffer_inv sc1
	global_load_dword v2, v3, s[8:9] sc1
	s_waitcnt vmcnt(0)
	v_cmp_lt_u32_e32 vcc, v2, v1
	s_and_saveexec_b64 s[8:9], vcc
	s_cbranch_execz .LBB11_408
	s_mov_b32 s1, 1
	s_mov_b64 s[10:11], 0
	s_branch .LBB11_399

; __device__ __forceinline__ unsigned xb_ld(unsigned* p)              { return __hip_atomic_load(p, __ATOMIC_RELAXED, __HIP_MEMORY_SCOPE_AGENT); }
; #define XB_SPIN(cond, bar) do { unsigned _sp = 0; while (cond) { __builtin_amdgcn_s_sleep(1); \
;     if ((++_sp & 255u) == 0u) { if (xb_ld(&(bar)[XB_TMO])) break; if (_sp > XB_SPIN_CAP) { atomicAdd(&(bar)[XB_TMO], 1u); break; } } } } while (0)
; __device__ __forceinline__ void xcd_barrier(const XcdBarrier& b) {
;     ...
;             XB_SPIN(xb_ld(&bar[XB_XGEN(b.x)]) == gen, bar);
.LBB11_403:
	v_readlane_b32 s14, v250, 49
	v_readlane_b32 s15, v250, 50
	s_add_i32 s1, s1, 1
	s_mov_b64 s[16:17], -1
	s_nop 2
	global_load_dword v2, v3, s[14:15] sc1
	s_waitcnt vmcnt(0)
	v_cmp_ge_u32_e32 vcc, v2, v1
	s_orn2_b64 s[14:15], vcc, exec
	s_branch .LBB11_398

; __device__ __forceinline__ unsigned xb_ld(unsigned* p)              { return __hip_atomic_load(p, __ATOMIC_RELAXED, __HIP_MEMORY_SCOPE_AGENT); }
; __device__ __forceinline__ unsigned xb_add(unsigned* p, unsigned v) { return __hip_atomic_fetch_add(p, v, __ATOMIC_RELAXED, __HIP_MEMORY_SCOPE_AGENT); }
; #define XB_SPIN(cond, bar) do { unsigned _sp = 0; while (cond) { __builtin_amdgcn_s_sleep(1); \
;     if ((++_sp & 255u) == 0u) { if (xb_ld(&(bar)[XB_TMO])) break; if (_sp > XB_SPIN_CAP) { atomicAdd(&(bar)[XB_TMO], 1u); break; } } } } while (0)
; __device__ __forceinline__ void xcd_barrier(const XcdBarrier& b) {
;     ...
;             const unsigned og = xb_add(&bar[XB_TOP], 1u);
;             const unsigned tg = og / nx;
;             if (og + 1u == (tg + 1u) * nx) xb_add(&bar[XB_TOPGEN], 1u);
;             else XB_SPIN(xb_ld(&bar[XB_TOPGEN]) == tg, bar);
.LBB11_412:
	s_or_b64 exec, exec, s[8:9]
	s_waitcnt vmcnt(0)
	v_readfirstlane_b32 s1, v4
	v_sub_u32_e32 v5, 0, v2
	v_readlane_b32 s6, v250, 51
	v_add_u32_e32 v4, s1, v1
	v_cvt_f32_u32_e32 v1, v2
	v_readlane_b32 s7, v250, 52
	s_mov_b64 s[8:9], -1
	v_rcp_iflag_f32_e32 v1, v1
	s_nop 0
	v_mul_f32_e32 v1, 0x4f7ffffe, v1
	v_cvt_u32_f32_e32 v1, v1
	v_mul_lo_u32 v5, v5, v1
	v_mul_hi_u32 v5, v1, v5
	v_add_u32_e32 v1, v1, v5
	v_mul_hi_u32 v1, v4, v1
	v_mul_lo_u32 v5, v1, v2
	v_sub_u32_e32 v5, v4, v5
	v_cmp_ge_u32_e32 vcc, v5, v2
	v_add_u32_e32 v6, 1, v1
	v_add_u32_e32 v4, 1, v4
	v_cndmask_b32_e32 v1, v1, v6, vcc
	v_sub_u32_e32 v6, v5, v2
	v_cndmask_b32_e32 v5, v5, v6, vcc
	v_cmp_ge_u32_e32 vcc, v5, v2
	v_add_u32_e32 v5, 1, v1
	s_nop 0
	v_cndmask_b32_e32 v1, v1, v5, vcc
	v_mul_lo_u32 v5, v2, v1
	v_add_u32_e32 v2, v5, v2
	v_cmp_ne_u32_e32 vcc, v4, v2
	v_mov_b64_e32 v[4:5], s[6:7]
	s_and_saveexec_b64 s[6:7], vcc
	s_cbranch_execz .LBB11_441
	v_mov_b32_e32 v1, v2
	v_readlane_b32 s8, v250, 49
	v_readlane_b32 s9, v250, 50
	s_mov_b64 s[10:11], 0
	s_nop 3
	global_load_dword v2, v3, s[8:9] sc1
	s_waitcnt vmcnt(0)
	v_cmp_lt_u32_e32 vcc, v2, v1
	s_and_saveexec_b64 s[8:9], vcc
	s_cbranch_execz .LBB11_440
	s_mov_b32 s1, 1
	s_branch .LBB11_416

; __device__ __forceinline__ unsigned xb_ld(unsigned* p)              { return __hip_atomic_load(p, __ATOMIC_RELAXED, __HIP_MEMORY_SCOPE_AGENT); }
; #define XB_SPIN(cond, bar) do { unsigned _sp = 0; while (cond) { __builtin_amdgcn_s_sleep(1); \
;     if ((++_sp & 255u) == 0u) { if (xb_ld(&(bar)[XB_TMO])) break; if (_sp > XB_SPIN_CAP) { atomicAdd(&(bar)[XB_TMO], 1u); break; } } } } while (0)
; __device__ __forceinline__ void xcd_barrier(const XcdBarrier& b) {
;     ...
;             XB_SPIN(xb_ld(&bar[XB_XGEN(b.x)]) == gen, bar);
.LBB11_429:
	s_or_b64 exec, exec, s[4:5]
	v_cvt_f32_u32_e32 v6, v4
	s_waitcnt vmcnt(0)
	v_readfirstlane_b32 s1, v5
	v_sub_u32_e32 v5, 0, v4
	v_rcp_iflag_f32_e32 v6, v6
	v_add_u32_e32 v7, s1, v1
	v_mul_f32_e32 v6, 0x4f7ffffe, v6
	v_cvt_u32_f32_e32 v6, v6
	v_mul_lo_u32 v1, v5, v6
	v_mul_hi_u32 v1, v6, v1
	v_add_u32_e32 v1, v6, v1
	v_mul_hi_u32 v1, v7, v1
	v_mul_lo_u32 v5, v1, v4
	v_sub_u32_e32 v5, v7, v5
	v_add_u32_e32 v6, 1, v1
	v_cmp_ge_u32_e32 vcc, v5, v4
	s_nop 1
	v_cndmask_b32_e32 v1, v1, v6, vcc
	v_sub_u32_e32 v6, v5, v4
	v_cndmask_b32_e32 v5, v5, v6, vcc
	v_add_u32_e32 v6, 1, v1
	v_cmp_ge_u32_e32 vcc, v5, v4
	v_add_u32_e32 v5, 1, v7
	s_nop 0
	v_cndmask_b32_e32 v1, v1, v6, vcc
	v_mul_lo_u32 v6, v4, v1
	v_add_u32_e32 v4, v6, v4
	v_cmp_ne_u32_e32 vcc, v5, v4
	s_and_saveexec_b64 s[4:5], vcc
	s_xor_b64 s[4:5], exec, s[4:5]
	s_cbranch_execz .LBB11_604
	v_readlane_b32 s101, v255, 13
	v_readlane_b32 s8, v255, 14
	s_nop 3
	s_cmp_eq_u32 s100, 1
	s_cselect_b32 s101, s8, s101
	s_cselect_b32 s8, 1, 3
	s_add_i32 s101, s101, 1
	s_lshl_b32 s101, s101, s8
	v_mov_b32_e32 v1, s101
	v_readlane_b32 s8, v250, 49
	v_readlane_b32 s9, v250, 50
	s_waitcnt lgkmcnt(0)
	s_nop 3
	buffer_inv sc1
	global_load_dword v2, v3, s[8:9] sc1
	s_waitcnt vmcnt(0)
	v_cmp_lt_u32_e32 vcc, v2, v1
	s_and_saveexec_b64 s[8:9], vcc
	s_cbranch_execz .LBB11_603
	s_mov_b32 s1, 1
	s_mov_b64 s[10:11], 0
	s_branch .LBB11_433

; __device__ __forceinline__ unsigned xb_ld(unsigned* p)              { return __hip_atomic_load(p, __ATOMIC_RELAXED, __HIP_MEMORY_SCOPE_AGENT); }
; __device__ __forceinline__ unsigned xb_add(unsigned* p, unsigned v) { return __hip_atomic_fetch_add(p, v, __ATOMIC_RELAXED, __HIP_MEMORY_SCOPE_AGENT); }
; #define XB_SPIN(cond, bar) do { unsigned _sp = 0; while (cond) { __builtin_amdgcn_s_sleep(1); \
;     if ((++_sp & 255u) == 0u) { if (xb_ld(&(bar)[XB_TMO])) break; if (_sp > XB_SPIN_CAP) { atomicAdd(&(bar)[XB_TMO], 1u); break; } } } } while (0)
; __device__ __forceinline__ void xcd_barrier(const XcdBarrier& b) {
;     ...
;             const unsigned og = xb_add(&bar[XB_TOP], 1u);
;             const unsigned tg = og / nx;
;             if (og + 1u == (tg + 1u) * nx) xb_add(&bar[XB_TOPGEN], 1u);
;             else XB_SPIN(xb_ld(&bar[XB_TOPGEN]) == tg, bar);
.LBB11_607:
	s_or_b64 exec, exec, s[8:9]
	s_waitcnt vmcnt(0)
	v_readfirstlane_b32 s1, v4
	v_sub_u32_e32 v5, 0, v2
	v_readlane_b32 s4, v250, 51
	v_add_u32_e32 v4, s1, v1
	v_cvt_f32_u32_e32 v1, v2
	v_readlane_b32 s5, v250, 52
	s_mov_b64 s[8:9], -1
	v_rcp_iflag_f32_e32 v1, v1
	s_nop 0
	v_mul_f32_e32 v1, 0x4f7ffffe, v1
	v_cvt_u32_f32_e32 v1, v1
	v_mul_lo_u32 v5, v5, v1
	v_mul_hi_u32 v5, v1, v5
	v_add_u32_e32 v1, v1, v5
	v_mul_hi_u32 v1, v4, v1
	v_mul_lo_u32 v5, v1, v2
	v_sub_u32_e32 v5, v4, v5
	v_cmp_ge_u32_e32 vcc, v5, v2
	v_add_u32_e32 v6, 1, v1
	v_add_u32_e32 v4, 1, v4
	v_cndmask_b32_e32 v1, v1, v6, vcc
	v_sub_u32_e32 v6, v5, v2
	v_cndmask_b32_e32 v5, v5, v6, vcc
	v_cmp_ge_u32_e32 vcc, v5, v2
	v_add_u32_e32 v5, 1, v1
	s_nop 0
	v_cndmask_b32_e32 v1, v1, v5, vcc
	v_mul_lo_u32 v5, v2, v1
	v_add_u32_e32 v2, v5, v2
	v_cmp_ne_u32_e32 vcc, v4, v2
	v_mov_b64_e32 v[4:5], s[4:5]
	s_and_saveexec_b64 s[4:5], vcc
	s_cbranch_execz .LBB11_619
	v_mov_b32_e32 v1, v2
	v_readlane_b32 s8, v250, 49
	v_readlane_b32 s9, v250, 50
	s_mov_b64 s[10:11], 0
	s_nop 3
	global_load_dword v2, v3, s[8:9] sc1
	s_waitcnt vmcnt(0)
	v_cmp_lt_u32_e32 vcc, v2, v1
	s_and_saveexec_b64 s[8:9], vcc
	s_cbranch_execz .LBB11_618
	s_mov_b32 s1, 1
	s_branch .LBB11_611

; __device__ __forceinline__ unsigned xb_ld(unsigned* p)              { return __hip_atomic_load(p, __ATOMIC_RELAXED, __HIP_MEMORY_SCOPE_AGENT); }
; #define XB_SPIN(cond, bar) do { unsigned _sp = 0; while (cond) { __builtin_amdgcn_s_sleep(1); \
;     if ((++_sp & 255u) == 0u) { if (xb_ld(&(bar)[XB_TMO])) break; if (_sp > XB_SPIN_CAP) { atomicAdd(&(bar)[XB_TMO], 1u); break; } } } } while (0)
; __device__ __forceinline__ void xcd_barrier(const XcdBarrier& b) {
;     ...
;             XB_SPIN(xb_ld(&bar[XB_XGEN(b.x)]) == gen, bar);
.LBB11_869:
	s_or_b64 exec, exec, s[4:5]
	v_cvt_f32_u32_e32 v6, v4
	s_waitcnt vmcnt(0)
	v_readfirstlane_b32 s1, v5
	v_sub_u32_e32 v5, 0, v4
	v_rcp_iflag_f32_e32 v6, v6
	v_add_u32_e32 v7, s1, v1
	v_mul_f32_e32 v6, 0x4f7ffffe, v6
	v_cvt_u32_f32_e32 v6, v6
	v_mul_lo_u32 v1, v5, v6
	v_mul_hi_u32 v1, v6, v1
	v_add_u32_e32 v1, v6, v1
	v_mul_hi_u32 v1, v7, v1
	v_mul_lo_u32 v5, v1, v4
	v_sub_u32_e32 v5, v7, v5
	v_add_u32_e32 v6, 1, v1
	v_cmp_ge_u32_e32 vcc, v5, v4
	s_nop 1
	v_cndmask_b32_e32 v1, v1, v6, vcc
	v_sub_u32_e32 v6, v5, v4
	v_cndmask_b32_e32 v5, v5, v6, vcc
	v_add_u32_e32 v6, 1, v1
	v_cmp_ge_u32_e32 vcc, v5, v4
	v_add_u32_e32 v5, 1, v7
	s_nop 0
	v_cndmask_b32_e32 v1, v1, v6, vcc
	v_mul_lo_u32 v6, v4, v1
	v_add_u32_e32 v4, v6, v4
	v_cmp_ne_u32_e32 vcc, v5, v4
	s_and_saveexec_b64 s[4:5], vcc
	s_xor_b64 s[4:5], exec, s[4:5]
	s_cbranch_execz .LBB11_883
	v_readlane_b32 s101, v255, 13
	v_readlane_b32 s6, v255, 14
	s_nop 3
	s_cmp_eq_u32 s100, 1
	s_cselect_b32 s101, s6, s101
	s_cselect_b32 s6, 1, 3
	s_add_i32 s101, s101, 1
	s_lshl_b32 s101, s101, s6
	v_mov_b32_e32 v1, s101
	v_readlane_b32 s6, v250, 49
	v_readlane_b32 s7, v250, 50
	s_waitcnt lgkmcnt(0)
	s_nop 3
	buffer_inv sc1
	global_load_dword v2, v3, s[6:7] sc1
	s_waitcnt vmcnt(0)
	v_cmp_lt_u32_e32 vcc, v2, v1
	s_and_saveexec_b64 s[6:7], vcc
	s_cbranch_execz .LBB11_882
	s_mov_b32 s1, 1
	s_mov_b64 s[8:9], 0
	s_branch .LBB11_873

; __device__ __forceinline__ unsigned xb_ld(unsigned* p)              { return __hip_atomic_load(p, __ATOMIC_RELAXED, __HIP_MEMORY_SCOPE_AGENT); }
; #define XB_SPIN(cond, bar) do { unsigned _sp = 0; while (cond) { __builtin_amdgcn_s_sleep(1); \
;     if ((++_sp & 255u) == 0u) { if (xb_ld(&(bar)[XB_TMO])) break; if (_sp > XB_SPIN_CAP) { atomicAdd(&(bar)[XB_TMO], 1u); break; } } } } while (0)
; __device__ __forceinline__ void xcd_barrier(const XcdBarrier& b) {
;     ...
;             XB_SPIN(xb_ld(&bar[XB_XGEN(b.x)]) == gen, bar);
.LBB11_877:
	v_readlane_b32 s12, v250, 49
	v_readlane_b32 s13, v250, 50
	s_add_i32 s1, s1, 1
	s_mov_b64 s[14:15], -1
	s_nop 2
	global_load_dword v2, v3, s[12:13] sc1
	s_waitcnt vmcnt(0)
	v_cmp_ge_u32_e32 vcc, v2, v1
	s_orn2_b64 s[12:13], vcc, exec
	s_branch .LBB11_872

; __device__ __forceinline__ unsigned xb_ld(unsigned* p)              { return __hip_atomic_load(p, __ATOMIC_RELAXED, __HIP_MEMORY_SCOPE_AGENT); }
; __device__ __forceinline__ unsigned xb_add(unsigned* p, unsigned v) { return __hip_atomic_fetch_add(p, v, __ATOMIC_RELAXED, __HIP_MEMORY_SCOPE_AGENT); }
; #define XB_SPIN(cond, bar) do { unsigned _sp = 0; while (cond) { __builtin_amdgcn_s_sleep(1); \
;     if ((++_sp & 255u) == 0u) { if (xb_ld(&(bar)[XB_TMO])) break; if (_sp > XB_SPIN_CAP) { atomicAdd(&(bar)[XB_TMO], 1u); break; } } } } while (0)
; __device__ __forceinline__ void xcd_barrier(const XcdBarrier& b) {
;     ...
;             const unsigned og = xb_add(&bar[XB_TOP], 1u);
;             const unsigned tg = og / nx;
;             if (og + 1u == (tg + 1u) * nx) xb_add(&bar[XB_TOPGEN], 1u);
;             else XB_SPIN(xb_ld(&bar[XB_TOPGEN]) == tg, bar);
.LBB11_886:
	s_or_b64 exec, exec, s[6:7]
	s_waitcnt vmcnt(0)
	v_readfirstlane_b32 s1, v4
	v_sub_u32_e32 v5, 0, v2
	v_readlane_b32 s4, v250, 51
	v_add_u32_e32 v4, s1, v1
	v_cvt_f32_u32_e32 v1, v2
	v_readlane_b32 s5, v250, 52
	s_mov_b64 s[6:7], -1
	v_rcp_iflag_f32_e32 v1, v1
	s_nop 0
	v_mul_f32_e32 v1, 0x4f7ffffe, v1
	v_cvt_u32_f32_e32 v1, v1
	v_mul_lo_u32 v5, v5, v1
	v_mul_hi_u32 v5, v1, v5
	v_add_u32_e32 v1, v1, v5
	v_mul_hi_u32 v1, v4, v1
	v_mul_lo_u32 v5, v1, v2
	v_sub_u32_e32 v5, v4, v5
	v_cmp_ge_u32_e32 vcc, v5, v2
	v_add_u32_e32 v6, 1, v1
	v_add_u32_e32 v4, 1, v4
	v_cndmask_b32_e32 v1, v1, v6, vcc
	v_sub_u32_e32 v6, v5, v2
	v_cndmask_b32_e32 v5, v5, v6, vcc
	v_cmp_ge_u32_e32 vcc, v5, v2
	v_add_u32_e32 v5, 1, v1
	s_nop 0
	v_cndmask_b32_e32 v1, v1, v5, vcc
	v_mul_lo_u32 v5, v2, v1
	v_add_u32_e32 v2, v5, v2
	v_cmp_ne_u32_e32 vcc, v4, v2
	v_mov_b64_e32 v[4:5], s[4:5]
	s_and_saveexec_b64 s[4:5], vcc
	s_cbranch_execz .LBB11_898
	v_mov_b32_e32 v1, v2
	v_readlane_b32 s6, v250, 49
	v_readlane_b32 s7, v250, 50
	s_mov_b64 s[8:9], 0
	s_nop 3
	global_load_dword v2, v3, s[6:7] sc1
	s_waitcnt vmcnt(0)
	v_cmp_lt_u32_e32 vcc, v2, v1
	s_and_saveexec_b64 s[6:7], vcc
	s_cbranch_execz .LBB11_897
	s_mov_b32 s1, 1
	s_branch .LBB11_890

; __device__ __forceinline__ unsigned xb_ld(unsigned* p)              { return __hip_atomic_load(p, __ATOMIC_RELAXED, __HIP_MEMORY_SCOPE_AGENT); }
; #define XB_SPIN(cond, bar) do { unsigned _sp = 0; while (cond) { __builtin_amdgcn_s_sleep(1); \
;     if ((++_sp & 255u) == 0u) { if (xb_ld(&(bar)[XB_TMO])) break; if (_sp > XB_SPIN_CAP) { atomicAdd(&(bar)[XB_TMO], 1u); break; } } } } while (0)
; __device__ __forceinline__ void xcd_barrier(const XcdBarrier& b) {
;     ...
;             XB_SPIN(xb_ld(&bar[XB_XGEN(b.x)]) == gen, bar);
.LBB11_1845:
	s_or_b64 exec, exec, s[4:5]
	v_cvt_f32_u32_e32 v6, v4
	s_waitcnt vmcnt(0)
	v_readfirstlane_b32 s1, v5
	v_sub_u32_e32 v5, 0, v4
	v_rcp_iflag_f32_e32 v6, v6
	v_add_u32_e32 v7, s1, v1
	v_mul_f32_e32 v6, 0x4f7ffffe, v6
	v_cvt_u32_f32_e32 v6, v6
	v_mul_lo_u32 v1, v5, v6
	v_mul_hi_u32 v1, v6, v1
	v_add_u32_e32 v1, v6, v1
	v_mul_hi_u32 v1, v7, v1
	v_mul_lo_u32 v5, v1, v4
	v_sub_u32_e32 v5, v7, v5
	v_add_u32_e32 v6, 1, v1
	v_cmp_ge_u32_e32 vcc, v5, v4
	s_nop 1
	v_cndmask_b32_e32 v1, v1, v6, vcc
	v_sub_u32_e32 v6, v5, v4
	v_cndmask_b32_e32 v5, v5, v6, vcc
	v_add_u32_e32 v6, 1, v1
	v_cmp_ge_u32_e32 vcc, v5, v4
	v_add_u32_e32 v5, 1, v7
	s_nop 0
	v_cndmask_b32_e32 v1, v1, v6, vcc
	v_mul_lo_u32 v6, v4, v1
	v_add_u32_e32 v4, v6, v4
	v_cmp_ne_u32_e32 vcc, v5, v4
	s_and_saveexec_b64 s[4:5], vcc
	s_xor_b64 s[4:5], exec, s[4:5]
	s_cbranch_execz .LBB11_1859
	v_readlane_b32 s101, v255, 13
	v_readlane_b32 s14, v255, 14
	s_nop 3
	s_cmp_eq_u32 s100, 1
	s_cselect_b32 s101, s14, s101
	s_cselect_b32 s14, 1, 3
	s_add_i32 s101, s101, 1
	s_lshl_b32 s101, s101, s14
	v_mov_b32_e32 v1, s101
	v_readlane_b32 s14, v250, 49
	v_readlane_b32 s15, v250, 50
	s_waitcnt lgkmcnt(0)
	s_nop 3
	buffer_inv sc1
	global_load_dword v2, v3, s[14:15] sc1
	s_waitcnt vmcnt(0)
	v_cmp_lt_u32_e32 vcc, v2, v1
	s_and_saveexec_b64 s[14:15], vcc
	s_cbranch_execz .LBB11_1858
	s_mov_b32 s1, 1
	s_mov_b64 s[16:17], 0
	s_branch .LBB11_1849

; __device__ __forceinline__ unsigned xb_ld(unsigned* p)              { return __hip_atomic_load(p, __ATOMIC_RELAXED, __HIP_MEMORY_SCOPE_AGENT); }
; #define XB_SPIN(cond, bar) do { unsigned _sp = 0; while (cond) { __builtin_amdgcn_s_sleep(1); \
;     if ((++_sp & 255u) == 0u) { if (xb_ld(&(bar)[XB_TMO])) break; if (_sp > XB_SPIN_CAP) { atomicAdd(&(bar)[XB_TMO], 1u); break; } } } } while (0)
; __device__ __forceinline__ void xcd_barrier(const XcdBarrier& b) {
;     ...
;             XB_SPIN(xb_ld(&bar[XB_XGEN(b.x)]) == gen, bar);
.LBB11_1853:
	v_readlane_b32 s20, v250, 49
	v_readlane_b32 s21, v250, 50
	s_add_i32 s1, s1, 1
	s_mov_b64 s[22:23], -1
	s_nop 2
	global_load_dword v2, v3, s[20:21] sc1
	s_waitcnt vmcnt(0)
	v_cmp_ge_u32_e32 vcc, v2, v1
	s_orn2_b64 s[20:21], vcc, exec
	s_branch .LBB11_1848

; __device__ __forceinline__ unsigned xb_ld(unsigned* p)              { return __hip_atomic_load(p, __ATOMIC_RELAXED, __HIP_MEMORY_SCOPE_AGENT); }
; __device__ __forceinline__ unsigned xb_add(unsigned* p, unsigned v) { return __hip_atomic_fetch_add(p, v, __ATOMIC_RELAXED, __HIP_MEMORY_SCOPE_AGENT); }
; #define XB_SPIN(cond, bar) do { unsigned _sp = 0; while (cond) { __builtin_amdgcn_s_sleep(1); \
;     if ((++_sp & 255u) == 0u) { if (xb_ld(&(bar)[XB_TMO])) break; if (_sp > XB_SPIN_CAP) { atomicAdd(&(bar)[XB_TMO], 1u); break; } } } } while (0)
; __device__ __forceinline__ void xcd_barrier(const XcdBarrier& b) {
;     ...
;         const unsigned old = xb_add(&bar[XB_XSUB(b.x)], 1u);
;         const unsigned gen = old / nloc;
;         if (old + 1u == (gen + 1u) * nloc) {
;             __builtin_amdgcn_fence(__ATOMIC_RELEASE, "agent");
;             asm volatile("s_waitcnt vmcnt(0)" ::: "memory");
;             const unsigned og = xb_add(&bar[XB_TOP], 1u);
;             const unsigned tg = og / nx;
;             if (og + 1u == (tg + 1u) * nx) xb_add(&bar[XB_TOPGEN], 1u);
;             else XB_SPIN(xb_ld(&bar[XB_TOPGEN]) == tg, bar);
;             __builtin_amdgcn_fence(__ATOMIC_ACQUIRE, "agent");
;             xb_add(&bar[XB_XGEN(b.x)], 1u);
;             asm volatile("s_waitcnt vmcnt(0)" ::: "memory");
;         } else {
;             XB_SPIN(xb_ld(&bar[XB_XGEN(b.x)]) == gen, bar);
.LBB11_1862:
	s_or_b64 exec, exec, s[14:15]
	s_waitcnt vmcnt(0)
	v_readfirstlane_b32 s1, v4
	v_sub_u32_e32 v5, 0, v2
	v_readlane_b32 s4, v250, 51
	v_add_u32_e32 v4, s1, v1
	v_cvt_f32_u32_e32 v1, v2
	v_readlane_b32 s5, v250, 52
	s_mov_b64 s[14:15], -1
	v_rcp_iflag_f32_e32 v1, v1
	s_nop 0
	v_mul_f32_e32 v1, 0x4f7ffffe, v1
	v_cvt_u32_f32_e32 v1, v1
	v_mul_lo_u32 v5, v5, v1
	v_mul_hi_u32 v5, v1, v5
	v_add_u32_e32 v1, v1, v5
	v_mul_hi_u32 v1, v4, v1
	v_mul_lo_u32 v5, v1, v2
	v_sub_u32_e32 v5, v4, v5
	v_cmp_ge_u32_e32 vcc, v5, v2
	v_add_u32_e32 v6, 1, v1
	v_add_u32_e32 v4, 1, v4
	v_cndmask_b32_e32 v1, v1, v6, vcc
	v_sub_u32_e32 v6, v5, v2
	v_cndmask_b32_e32 v5, v5, v6, vcc
	v_cmp_ge_u32_e32 vcc, v5, v2
	v_add_u32_e32 v5, 1, v1
	s_nop 0
	v_cndmask_b32_e32 v1, v1, v5, vcc
	v_mul_lo_u32 v5, v2, v1
	v_add_u32_e32 v2, v5, v2
	v_cmp_ne_u32_e32 vcc, v4, v2
	v_mov_b64_e32 v[4:5], s[4:5]
	s_and_saveexec_b64 s[4:5], vcc
	s_cbranch_execz .LBB11_1874
	v_mov_b32_e32 v1, v2
	v_readlane_b32 s14, v250, 49
	v_readlane_b32 s15, v250, 50
	s_mov_b64 s[16:17], 0
	s_nop 3
	global_load_dword v2, v3, s[14:15] sc1
	s_waitcnt vmcnt(0)
	v_cmp_lt_u32_e32 vcc, v2, v1
	s_and_saveexec_b64 s[14:15], vcc
	s_cbranch_execz .LBB11_1873
	s_mov_b32 s1, 1
	s_branch .LBB11_1866
